# s_setprio 1/0 around QK and PV MFMA clusters in prompt attention loop
# speedup vs baseline: 1.0014x; 1.0014x over previous
.LBB0_1134:
	s_waitcnt lgkmcnt(0)
	s_setprio 1
	v_mfma_f32_32x32x16_bf16 v[64:79], v[112:115], v[80:83], 0
	s_cmp_gt_u32 s81, 3
	s_cselect_b64 s[2:3], -1, 0
	s_and_b64 vcc, exec, s[2:3]
	v_mfma_f32_32x32x16_bf16 v[64:79], v[116:119], v[84:87], v[64:79]
	v_mfma_f32_32x32x16_bf16 v[64:79], v[120:123], v[88:91], v[64:79]
	v_mfma_f32_32x32x16_bf16 v[64:79], v[124:127], v[92:95], v[64:79]
	v_mfma_f32_32x32x16_bf16 v[64:79], v[128:131], v[96:99], v[64:79]
	v_mfma_f32_32x32x16_bf16 v[64:79], v[132:135], v[100:103], v[64:79]
	v_mfma_f32_32x32x16_bf16 v[64:79], v[136:139], v[104:107], v[64:79]
	v_mfma_f32_32x32x16_bf16 v[64:79], v[140:143], v[108:111], v[64:79]
	s_setprio 0
	s_cbranch_vccnz .LBB0_1136
	v_ashrrev_i32_e32 v116, 31, v149
	v_mov_b64_e32 v[112:113], s[84:85]
	v_mad_u64_u32 v[114:115], s[0:1], s74, v149, v[112:113]
	v_mul_lo_u32 v117, s75, v149
	v_mul_lo_u32 v116, s74, v116
	v_add3_u32 v115, v117, v115, v116
	v_lshlrev_b64 v[114:115], 8, v[114:115]
	v_lshl_add_u64 v[114:115], v[154:155], 0, v[114:115]
	s_mov_b32 m0, s90
	v_lshl_add_u64 v[116:117], v[114:115], 0, s[96:97]
	global_load_lds_dwordx4 v[114:115], off
	s_add_i32 m0, s90, 0x400
	v_lshl_add_u64 v[118:119], v[114:115], 0, 64
	global_load_lds_dwordx4 v[116:117], off
	s_add_i32 m0, s90, 0x800
	s_nop 0
	global_load_lds_dwordx4 v[118:119], off
	v_lshl_add_u64 v[118:119], v[116:117], 0, 64
	s_add_i32 m0, s90, 0xc00
	s_nop 0
	global_load_lds_dwordx4 v[118:119], off
	v_lshl_add_u64 v[118:119], v[114:115], 0, s[88:89]
	s_add_i32 m0, s90, 0x1000
	v_lshl_add_u64 v[114:115], v[114:115], 0, s[100:101]
	global_load_lds_dwordx4 v[118:119], off
	v_lshl_add_u64 v[118:119], v[116:117], 0, s[88:89]
	s_add_i32 m0, s90, 0x1400
	s_nop 0
	global_load_lds_dwordx4 v[118:119], off
	s_add_i32 m0, s90, 0x1800
	s_nop 0
	global_load_lds_dwordx4 v[114:115], off
	v_lshl_add_u64 v[114:115], v[116:117], 0, s[100:101]
	s_add_i32 m0, s90, 0x1c00
	s_nop 0
	global_load_lds_dwordx4 v[114:115], off

.LBB0_1145:
	v_add_f32_e32 v73, v73, v74
	v_fmac_f32_e32 v73, v171, v72
	v_add_u32_e32 v72, 0x2000, v166
	ds_read_b64_tr_b16 v[180:181], v72 offset:0
	ds_read_b64_tr_b16 v[182:183], v72 offset:0+512
	ds_read_b64_tr_b16 v[176:177], v72 offset:0+1024
	ds_read_b64_tr_b16 v[178:179], v72 offset:0+1536
	ds_read_b64_tr_b16 v[172:173], v72 offset:0+2048
	ds_read_b64_tr_b16 v[174:175], v72 offset:0+2560
	ds_read_b64_tr_b16 v[74:75], v72 offset:0+3072
	ds_read_b64_tr_b16 v[76:77], v72 offset:0+3584
	s_waitcnt lgkmcnt(0)
	s_add_i32 s81, s81, 1
	s_setprio 1
	v_mfma_f32_32x32x16_bf16 v[48:63], v[180:183], v[64:67], v[48:63]
	s_xor_b32 s78, s78, 1
	v_add_u32_e32 v147, 32, v147
	s_andn2_b64 vcc, exec, s[2:3]
	v_mfma_f32_32x32x16_bf16 v[32:47], v[172:175], v[64:67], v[32:47]
	v_mfma_f32_32x32x16_bf16 v[48:63], v[176:179], v[68:71], v[48:63]
	v_mfma_f32_32x32x16_bf16 v[32:47], v[74:77], v[68:71], v[32:47]
	s_setprio 0
	ds_read_b64_tr_b16 v[180:181], v72 offset:0x1000
	ds_read_b64_tr_b16 v[182:183], v72 offset:0x1000+512
	ds_read_b64_tr_b16 v[176:177], v72 offset:0x1000+1024
	ds_read_b64_tr_b16 v[178:179], v72 offset:0x1000+1536
	ds_read_b64_tr_b16 v[172:173], v72 offset:0x1000+2048
	ds_read_b64_tr_b16 v[174:175], v72 offset:0x1000+2560
	ds_read_b64_tr_b16 v[74:75], v72 offset:0x1000+3072
	ds_read_b64_tr_b16 v[76:77], v72 offset:0x1000+3584
	s_waitcnt lgkmcnt(0)
	s_nop 0
	s_setprio 1
	v_mfma_f32_32x32x16_bf16 v[16:31], v[180:183], v[64:67], v[16:31]
	v_mfma_f32_32x32x16_bf16 v[0:15], v[172:175], v[64:67], v[0:15]
	v_mfma_f32_32x32x16_bf16 v[16:31], v[176:179], v[68:71], v[16:31]
	v_mfma_f32_32x32x16_bf16 v[0:15], v[74:77], v[68:71], v[0:15]
	s_setprio 0
	s_cbranch_vccz .LBB0_1148
	v_mov_b32_e32 v171, v73
	v_mov_b32_e32 v172, v145
	s_waitcnt vmcnt(0)
	ds_read_b128 v[112:115], v196
	ds_read_b128 v[116:119], v197
	ds_read_b128 v[120:123], v196 offset:2048
	ds_read_b128 v[124:127], v197 offset:2048
	ds_read_b128 v[128:131], v196 offset:4096
	ds_read_b128 v[132:135], v197 offset:4096
	ds_read_b128 v[136:139], v196 offset:6144
	ds_read_b128 v[140:143], v197 offset:6144
	v_ashrrev_i32_e32 v180, 31, v149
	v_mov_b64_e32 v[176:177], s[84:85]
	v_mad_u64_u32 v[178:179], s[0:1], s74, v149, v[176:177]
	v_mul_lo_u32 v181, s75, v149
	v_mul_lo_u32 v180, s74, v180
	v_add3_u32 v179, v181, v179, v180
	v_lshlrev_b64 v[178:179], 8, v[178:179]
	v_lshl_add_u64 v[178:179], v[152:153], 0, v[178:179]
	s_add_i32 m0, s90, 0x2000
	v_lshl_add_u64 v[180:181], v[178:179], 0, s[96:97]
	global_load_lds_dwordx4 v[178:179], off
	s_add_i32 m0, s90, 0x2400
	v_lshl_add_u64 v[182:183], v[178:179], 0, 64
	global_load_lds_dwordx4 v[180:181], off
	s_add_i32 m0, s90, 0x2800
	s_nop 0
	global_load_lds_dwordx4 v[182:183], off
	v_lshl_add_u64 v[182:183], v[180:181], 0, 64
	s_add_i32 m0, s90, 0x2c00
	s_nop 0
	global_load_lds_dwordx4 v[182:183], off
	v_lshl_add_u64 v[182:183], v[178:179], 0, s[88:89]
	s_add_i32 m0, s90, 0x3000
	v_lshl_add_u64 v[178:179], v[178:179], 0, s[100:101]
	global_load_lds_dwordx4 v[182:183], off
	v_lshl_add_u64 v[182:183], v[180:181], 0, s[88:89]
	s_add_i32 m0, s90, 0x3400
	s_nop 0
	global_load_lds_dwordx4 v[182:183], off
	s_add_i32 m0, s90, 0x3800
	s_nop 0
	global_load_lds_dwordx4 v[178:179], off
	v_lshl_add_u64 v[178:179], v[180:181], 0, s[100:101]
	s_add_i32 m0, s90, 0x3c00
	s_nop 0
	global_load_lds_dwordx4 v[178:179], off
	v_add_u32_e32 v149, 32, v149
	s_branch .LBB0_1134
